# speedup vs baseline: 1.0146x; 1.0032x over previous
; __device__ __forceinline__ void dsa_item(const Params& p, int tk0) {
;     ...
;   unsigned T = 0; bool exact = false;
;   if (qpos + 1 > 256) {
;     unsigned um = 0;
; #pragma unroll
;     for (int j = 0; j < 64; ++j) um = max(um, sc[j]);
;     um = __builtin_amdgcn_readfirstlane(wave_max_u(um));
;     unsigned df = 0;
; #pragma unroll
;     for (int j = 0; j < 64; ++j) df |= sc[j] ? (sc[j] ^ um) : 0u;
.LBB0_2425:
	v_pk_add_f32 v[2:3], v[16:17], v[18:19]
	v_or_b32_e32 v0, 64, v26
	v_and_b32_e32 v5, 0x7fffffff, v3
	v_and_b32_e32 v4, 0x7fffffff, v2
	v_xor_b32_e32 v6, -1, v2
	v_pk_add_f32 v[4:5], v[4:5], 0 neg_lo:[1,1] neg_hi:[1,1]
	v_cmp_gt_i32_e32 vcc, 0, v2
	v_xor_b32_e32 v1, -1, v3
	s_mov_b32 s57, 0
	v_cndmask_b32_e32 v4, v4, v6, vcc
	v_cmp_gt_i32_e32 vcc, 0, v3
	s_cmpk_gt_u32 s12, 0xff
	s_mov_b64 s[2:3], 0
	v_cndmask_b32_e32 v1, v5, v1, vcc
	v_cmp_ge_u32_e32 vcc, s12, v26
	s_nop 1
	v_cndmask_b32_e32 v2, 0, v1, vcc
	v_cmp_ge_u32_e32 vcc, s12, v0
	s_nop 1
	v_cndmask_b32_e32 v1, 0, v4, vcc
	s_cbranch_scc0 .LBB0_2436
	v_max_u32_e32 v3, v2, v1
	v_max3_u32 v3, v3, v28, v27
	v_max3_u32 v3, v3, v30, v29
	v_max3_u32 v3, v3, v32, v31
	v_max3_u32 v3, v3, v34, v33
	v_max3_u32 v3, v3, v36, v35
	v_max3_u32 v3, v3, v38, v37
	v_max3_u32 v3, v3, v40, v39
	v_max3_u32 v3, v3, v42, v41
	v_max3_u32 v3, v3, v44, v43
	v_max3_u32 v3, v3, v46, v45
	v_max3_u32 v3, v3, v48, v47
	v_max3_u32 v3, v3, v50, v49
	v_max3_u32 v3, v3, v52, v51
	v_max3_u32 v3, v3, v54, v53
	v_max3_u32 v3, v3, v60, v59
	v_max3_u32 v3, v3, v64, v63
	v_max3_u32 v3, v3, v66, v65
	v_max3_u32 v3, v3, v68, v67
	v_max3_u32 v3, v3, v70, v69
	v_max3_u32 v3, v3, v72, v71
	v_max3_u32 v3, v3, v74, v73
	v_max3_u32 v3, v3, v76, v75
	v_max3_u32 v3, v3, v78, v77
	v_max3_u32 v3, v3, v80, v79
	v_max3_u32 v3, v3, v82, v81
	v_max3_u32 v3, v3, v84, v83
	v_max3_u32 v3, v3, v86, v85
	v_max3_u32 v3, v3, v88, v87
	v_max3_u32 v3, v3, v25, v24
	v_max3_u32 v3, v3, v23, v22
	v_max3_u32 v3, v3, v9, v8
	v_cmp_ne_u32_e32 vcc, 0, v2
	s_nop 0
	v_max_u32_dpp v3, v3, v3 quad_perm:[1,0,3,2] row_mask:0xf bank_mask:0xf bound_ctrl:1
	s_nop 1
	v_max_u32_dpp v3, v3, v3 quad_perm:[2,3,0,1] row_mask:0xf bank_mask:0xf bound_ctrl:1
	s_nop 1
	v_max_u32_dpp v3, v3, v3 row_half_mirror row_mask:0xf bank_mask:0xf bound_ctrl:1
	s_nop 1
	v_max_u32_dpp v3, v3, v3 row_mirror row_mask:0xf bank_mask:0xf bound_ctrl:1
	v_mov_b32_e32 v4, v3
	s_nop 1
	v_permlane16_swap_b32_e32 v3, v4
	v_max_u32_e32 v3, v3, v4
	v_mov_b32_e32 v4, v3
	s_nop 1
	v_permlane32_swap_b32_e32 v3, v4
	v_max_u32_e32 v3, v3, v4
	s_nop 0
	v_readfirstlane_b32 s2, v3
	s_nop 1
	v_xor_b32_e32 v3, s2, v2
	v_cndmask_b32_e32 v3, 0, v3, vcc
	v_xor_b32_e32 v4, s2, v1
	v_cmp_ne_u32_e32 vcc, 0, v1
	v_xor_b32_e32 v5, s2, v27
	s_nop 0
	v_cndmask_b32_e32 v4, 0, v4, vcc
	v_or_b32_e32 v3, v4, v3
	v_xor_b32_e32 v4, s2, v28
	v_cmp_ne_u32_e32 vcc, 0, v28
	s_nop 1
	v_cndmask_b32_e32 v4, 0, v4, vcc
	v_cmp_ne_u32_e32 vcc, 0, v27
	s_nop 1
	v_cndmask_b32_e32 v5, 0, v5, vcc
	v_or3_b32 v3, v3, v4, v5
	v_xor_b32_e32 v4, s2, v30
	v_cmp_ne_u32_e32 vcc, 0, v30
	v_xor_b32_e32 v5, s2, v29
	s_nop 0
	v_cndmask_b32_e32 v4, 0, v4, vcc
	v_cmp_ne_u32_e32 vcc, 0, v29
	s_nop 1
	v_cndmask_b32_e32 v5, 0, v5, vcc
	v_or3_b32 v3, v3, v4, v5
	v_xor_b32_e32 v4, s2, v32
	v_cmp_ne_u32_e32 vcc, 0, v32
	v_xor_b32_e32 v5, s2, v31
	s_nop 0
	v_cndmask_b32_e32 v4, 0, v4, vcc
	v_cmp_ne_u32_e32 vcc, 0, v31
	s_nop 1
	v_cndmask_b32_e32 v5, 0, v5, vcc
	v_or3_b32 v3, v3, v4, v5
	v_xor_b32_e32 v4, s2, v34
	v_cmp_ne_u32_e32 vcc, 0, v34
	v_xor_b32_e32 v5, s2, v33
	s_nop 0
	v_cndmask_b32_e32 v4, 0, v4, vcc
	v_cmp_ne_u32_e32 vcc, 0, v33
	s_nop 1
	v_cndmask_b32_e32 v5, 0, v5, vcc
	v_or3_b32 v3, v3, v4, v5
	v_xor_b32_e32 v4, s2, v36
	v_cmp_ne_u32_e32 vcc, 0, v36
	v_xor_b32_e32 v5, s2, v35
	s_nop 0
	v_cndmask_b32_e32 v4, 0, v4, vcc
	v_cmp_ne_u32_e32 vcc, 0, v35
	s_nop 1
	v_cndmask_b32_e32 v5, 0, v5, vcc
	v_or3_b32 v3, v3, v4, v5
	v_xor_b32_e32 v4, s2, v38
	v_cmp_ne_u32_e32 vcc, 0, v38
	v_xor_b32_e32 v5, s2, v37
	s_nop 0
	v_cndmask_b32_e32 v4, 0, v4, vcc
	v_cmp_ne_u32_e32 vcc, 0, v37
	s_nop 1
	v_cndmask_b32_e32 v5, 0, v5, vcc
	v_or3_b32 v3, v3, v4, v5
	v_xor_b32_e32 v4, s2, v40
	v_cmp_ne_u32_e32 vcc, 0, v40
	v_xor_b32_e32 v5, s2, v39
	s_nop 0
	v_cndmask_b32_e32 v4, 0, v4, vcc
	v_cmp_ne_u32_e32 vcc, 0, v39
	s_nop 1
	v_cndmask_b32_e32 v5, 0, v5, vcc
	v_or3_b32 v3, v3, v4, v5
	v_xor_b32_e32 v4, s2, v42
	v_cmp_ne_u32_e32 vcc, 0, v42
	v_xor_b32_e32 v5, s2, v41
	s_nop 0
	v_cndmask_b32_e32 v4, 0, v4, vcc
	v_cmp_ne_u32_e32 vcc, 0, v41
	s_nop 1
	v_cndmask_b32_e32 v5, 0, v5, vcc
	v_or3_b32 v3, v3, v4, v5
	v_xor_b32_e32 v4, s2, v44
	v_cmp_ne_u32_e32 vcc, 0, v44
	v_xor_b32_e32 v5, s2, v43
	s_nop 0
	v_cndmask_b32_e32 v4, 0, v4, vcc
	v_cmp_ne_u32_e32 vcc, 0, v43
	s_nop 1
	v_cndmask_b32_e32 v5, 0, v5, vcc
	v_or3_b32 v3, v3, v4, v5
	v_xor_b32_e32 v4, s2, v46
	v_cmp_ne_u32_e32 vcc, 0, v46
	v_xor_b32_e32 v5, s2, v45
	s_nop 0
	v_cndmask_b32_e32 v4, 0, v4, vcc
	v_cmp_ne_u32_e32 vcc, 0, v45
	s_nop 1
	v_cndmask_b32_e32 v5, 0, v5, vcc
	v_or3_b32 v3, v3, v4, v5
	v_xor_b32_e32 v4, s2, v48
	v_cmp_ne_u32_e32 vcc, 0, v48
	v_xor_b32_e32 v5, s2, v47
	s_nop 0
	v_cndmask_b32_e32 v4, 0, v4, vcc
	v_cmp_ne_u32_e32 vcc, 0, v47
	s_nop 1
	v_cndmask_b32_e32 v5, 0, v5, vcc
	v_or3_b32 v3, v3, v4, v5
	v_xor_b32_e32 v4, s2, v50
	v_cmp_ne_u32_e32 vcc, 0, v50
	v_xor_b32_e32 v5, s2, v49
	s_nop 0
	v_cndmask_b32_e32 v4, 0, v4, vcc
	v_cmp_ne_u32_e32 vcc, 0, v49
	s_nop 1
	v_cndmask_b32_e32 v5, 0, v5, vcc
	v_or3_b32 v3, v3, v4, v5
	v_xor_b32_e32 v4, s2, v52
	v_cmp_ne_u32_e32 vcc, 0, v52
	v_xor_b32_e32 v5, s2, v51
	s_nop 0
	v_cndmask_b32_e32 v4, 0, v4, vcc
	v_cmp_ne_u32_e32 vcc, 0, v51
	s_nop 1
	v_cndmask_b32_e32 v5, 0, v5, vcc
	v_or3_b32 v3, v3, v4, v5
	v_xor_b32_e32 v4, s2, v54
	v_cmp_ne_u32_e32 vcc, 0, v54
	v_xor_b32_e32 v5, s2, v53
	s_nop 0
	v_cndmask_b32_e32 v4, 0, v4, vcc
	v_cmp_ne_u32_e32 vcc, 0, v53
	s_nop 1
	v_cndmask_b32_e32 v5, 0, v5, vcc
	v_or3_b32 v3, v3, v4, v5
	v_xor_b32_e32 v4, s2, v60
	v_cmp_ne_u32_e32 vcc, 0, v60
	v_xor_b32_e32 v5, s2, v59
	s_nop 0
	v_cndmask_b32_e32 v4, 0, v4, vcc
; __device__ __forceinline__ void dsa_item(const Params& p, int tk0) {
;     ...
;     for (int j = 0; j < 64; ++j) df |= sc[j] ? (sc[j] ^ um) : 0u;
;     df = __builtin_amdgcn_readfirstlane(wave_or_u(df));
;     const int hb = df ? (31 - __builtin_clz(df)) : -1;
;     T = (hb >= 31) ? 0u : (um & ~((2u << (hb < 0 ? 0 : hb)) - 1u));
;     if (hb < 0) T = um;
; #pragma unroll 1
;     ...
;       const unsigned cand = T | (1u << bit);
;       int c = 0;
; #pragma unroll
;       for (int j = 0; j < 16; ++j) c += (sc[j] >= cand) ? 1 : 0;
;       if (nblk > 16) {
; #pragma unroll
;         for (int j = 16; j < 32; ++j) c += (sc[j] >= cand) ? 1 : 0;
;       }
	v_cmp_ne_u32_e32 vcc, 0, v59
	s_nop 1
	v_cndmask_b32_e32 v5, 0, v5, vcc
	v_or3_b32 v3, v3, v4, v5
	v_xor_b32_e32 v4, s2, v64
	v_cmp_ne_u32_e32 vcc, 0, v64
	v_xor_b32_e32 v5, s2, v63
	s_nop 0
	v_cndmask_b32_e32 v4, 0, v4, vcc
	v_cmp_ne_u32_e32 vcc, 0, v63
	s_nop 1
	v_cndmask_b32_e32 v5, 0, v5, vcc
	v_or3_b32 v3, v3, v4, v5
	v_xor_b32_e32 v4, s2, v66
	v_cmp_ne_u32_e32 vcc, 0, v66
	v_xor_b32_e32 v5, s2, v65
	s_nop 0
	v_cndmask_b32_e32 v4, 0, v4, vcc
	v_cmp_ne_u32_e32 vcc, 0, v65
	s_nop 1
	v_cndmask_b32_e32 v5, 0, v5, vcc
	v_or3_b32 v3, v3, v4, v5
	v_xor_b32_e32 v4, s2, v68
	v_cmp_ne_u32_e32 vcc, 0, v68
	v_xor_b32_e32 v5, s2, v67
	s_nop 0
	v_cndmask_b32_e32 v4, 0, v4, vcc
	v_cmp_ne_u32_e32 vcc, 0, v67
	s_nop 1
	v_cndmask_b32_e32 v5, 0, v5, vcc
	v_or3_b32 v3, v3, v4, v5
	v_xor_b32_e32 v4, s2, v70
	v_cmp_ne_u32_e32 vcc, 0, v70
	v_xor_b32_e32 v5, s2, v69
	s_nop 0
	v_cndmask_b32_e32 v4, 0, v4, vcc
	v_cmp_ne_u32_e32 vcc, 0, v69
	s_nop 1
	v_cndmask_b32_e32 v5, 0, v5, vcc
	v_or3_b32 v3, v3, v4, v5
	v_xor_b32_e32 v4, s2, v72
	v_cmp_ne_u32_e32 vcc, 0, v72
	v_xor_b32_e32 v5, s2, v71
	s_nop 0
	v_cndmask_b32_e32 v4, 0, v4, vcc
	v_cmp_ne_u32_e32 vcc, 0, v71
	s_nop 1
	v_cndmask_b32_e32 v5, 0, v5, vcc
	v_or3_b32 v3, v3, v4, v5
	v_xor_b32_e32 v4, s2, v74
	v_cmp_ne_u32_e32 vcc, 0, v74
	v_xor_b32_e32 v5, s2, v73
	s_nop 0
	v_cndmask_b32_e32 v4, 0, v4, vcc
	v_cmp_ne_u32_e32 vcc, 0, v73
	s_nop 1
	v_cndmask_b32_e32 v5, 0, v5, vcc
	v_or3_b32 v3, v3, v4, v5
	v_xor_b32_e32 v4, s2, v76
	v_cmp_ne_u32_e32 vcc, 0, v76
	v_xor_b32_e32 v5, s2, v75
	s_nop 0
	v_cndmask_b32_e32 v4, 0, v4, vcc
	v_cmp_ne_u32_e32 vcc, 0, v75
	s_nop 1
	v_cndmask_b32_e32 v5, 0, v5, vcc
	v_or3_b32 v3, v3, v4, v5
	v_xor_b32_e32 v4, s2, v78
	v_cmp_ne_u32_e32 vcc, 0, v78
	v_xor_b32_e32 v5, s2, v77
	s_nop 0
	v_cndmask_b32_e32 v4, 0, v4, vcc
	v_cmp_ne_u32_e32 vcc, 0, v77
	s_nop 1
	v_cndmask_b32_e32 v5, 0, v5, vcc
	v_or3_b32 v3, v3, v4, v5
	v_xor_b32_e32 v4, s2, v80
	v_cmp_ne_u32_e32 vcc, 0, v80
	v_xor_b32_e32 v5, s2, v79
	s_nop 0
	v_cndmask_b32_e32 v4, 0, v4, vcc
	v_cmp_ne_u32_e32 vcc, 0, v79
	s_nop 1
	v_cndmask_b32_e32 v5, 0, v5, vcc
	v_or3_b32 v3, v3, v4, v5
	v_xor_b32_e32 v4, s2, v82
	v_cmp_ne_u32_e32 vcc, 0, v82
	v_xor_b32_e32 v5, s2, v81
	s_nop 0
	v_cndmask_b32_e32 v4, 0, v4, vcc
	v_cmp_ne_u32_e32 vcc, 0, v81
	s_nop 1
	v_cndmask_b32_e32 v5, 0, v5, vcc
	v_or3_b32 v3, v3, v4, v5
	v_xor_b32_e32 v4, s2, v84
	v_cmp_ne_u32_e32 vcc, 0, v84
	v_xor_b32_e32 v5, s2, v83
	s_nop 0
	v_cndmask_b32_e32 v4, 0, v4, vcc
	v_cmp_ne_u32_e32 vcc, 0, v83
	s_nop 1
	v_cndmask_b32_e32 v5, 0, v5, vcc
	v_or3_b32 v3, v3, v4, v5
	v_xor_b32_e32 v4, s2, v86
	v_cmp_ne_u32_e32 vcc, 0, v86
	v_xor_b32_e32 v5, s2, v85
	s_nop 0
	v_cndmask_b32_e32 v4, 0, v4, vcc
	v_cmp_ne_u32_e32 vcc, 0, v85
	s_nop 1
	v_cndmask_b32_e32 v5, 0, v5, vcc
	v_or3_b32 v3, v3, v4, v5
	v_xor_b32_e32 v4, s2, v88
	v_cmp_ne_u32_e32 vcc, 0, v88
	v_xor_b32_e32 v5, s2, v87
	s_nop 0
	v_cndmask_b32_e32 v4, 0, v4, vcc
	v_cmp_ne_u32_e32 vcc, 0, v87
	s_nop 1
	v_cndmask_b32_e32 v5, 0, v5, vcc
	v_or3_b32 v3, v3, v4, v5
	v_xor_b32_e32 v4, s2, v25
	v_cmp_ne_u32_e32 vcc, 0, v25
	v_xor_b32_e32 v5, s2, v24
	s_nop 0
	v_cndmask_b32_e32 v4, 0, v4, vcc
	v_cmp_ne_u32_e32 vcc, 0, v24
	s_nop 1
	v_cndmask_b32_e32 v5, 0, v5, vcc
	v_or3_b32 v3, v3, v4, v5
	v_xor_b32_e32 v4, s2, v23
	v_cmp_ne_u32_e32 vcc, 0, v23
	v_xor_b32_e32 v5, s2, v22
	s_nop 0
	v_cndmask_b32_e32 v4, 0, v4, vcc
	v_cmp_ne_u32_e32 vcc, 0, v22
	s_nop 1
	v_cndmask_b32_e32 v5, 0, v5, vcc
	v_or3_b32 v3, v3, v4, v5
	v_xor_b32_e32 v4, s2, v9
	v_cmp_ne_u32_e32 vcc, 0, v9
	v_xor_b32_e32 v5, s2, v8
	s_nop 0
	v_cndmask_b32_e32 v4, 0, v4, vcc
	v_cmp_ne_u32_e32 vcc, 0, v8
	s_nop 1
	v_cndmask_b32_e32 v5, 0, v5, vcc
	v_or3_b32 v3, v3, v4, v5
	s_nop 1
	v_or_b32_dpp v3, v3, v3 quad_perm:[1,0,3,2] row_mask:0xf bank_mask:0xf bound_ctrl:1
	s_nop 1
	v_or_b32_dpp v3, v3, v3 quad_perm:[2,3,0,1] row_mask:0xf bank_mask:0xf bound_ctrl:1
	s_nop 1
	v_or_b32_dpp v3, v3, v3 row_half_mirror row_mask:0xf bank_mask:0xf bound_ctrl:1
	s_nop 1
	v_or_b32_dpp v3, v3, v3 row_mirror row_mask:0xf bank_mask:0xf bound_ctrl:1
	v_mov_b32_e32 v4, v3
	s_nop 1
	v_permlane16_swap_b32_e32 v3, v4
	v_or_b32_e32 v3, v3, v4
	v_mov_b32_e32 v4, v3
	s_nop 1
	v_permlane32_swap_b32_e32 v3, v4
	v_or_b32_e32 v3, v3, v4
	s_nop 0
	v_readfirstlane_b32 s3, v3
	s_flbit_i32_b32 s11, s3
	s_xor_b32 s11, s11, 31
	s_lshl_b32 s12, -2, s11
	s_cmp_eq_u32 s3, 0
	s_cselect_b32 s12, -2, s12
	s_cselect_b32 s13, -1, s11
	s_and_b32 s12, s12, s2
	s_cmp_lt_i32 s13, 31
	s_cselect_b32 s12, s12, 0
	s_cmp_eq_u32 s3, 0
	s_cselect_b32 s57, s2, s12
	s_cmp_lt_i32 s13, 0
	s_cbranch_scc1 .LBB0_2435
	s_waitcnt vmcnt(0)
.LBB0_2427:
	s_lshl_b32 s2, 1, s11
	s_or_b32 s12, s2, s57
	v_mov_b32_e32 v3, 0
	v_cmp_le_u32_e32 vcc, s12, v1
	v_cmp_le_u32_e64 s[2:3], s12, v39
	v_cmp_le_u32_e64 s[98:99], s12, v2
	v_cmp_le_u32_e64 s[100:101], s12, v28
	v_addc_co_u32_e32 v3, vcc, 0, v3, vcc
	v_addc_co_u32_e64 v3, s[2:3], 0, v3, s[2:3]
	v_addc_co_u32_e64 v3, s[98:99], 0, v3, s[98:99]
	v_addc_co_u32_e64 v3, s[100:101], 0, v3, s[100:101]
	v_cmp_le_u32_e32 vcc, s12, v27
	v_cmp_le_u32_e64 s[2:3], s12, v30
	v_cmp_le_u32_e64 s[98:99], s12, v29
	v_cmp_le_u32_e64 s[100:101], s12, v32
	v_addc_co_u32_e32 v3, vcc, 0, v3, vcc
	v_addc_co_u32_e64 v3, s[2:3], 0, v3, s[2:3]
	v_addc_co_u32_e64 v3, s[98:99], 0, v3, s[98:99]
	v_addc_co_u32_e64 v3, s[100:101], 0, v3, s[100:101]
	v_cmp_le_u32_e32 vcc, s12, v31
	v_cmp_le_u32_e64 s[2:3], s12, v34
	v_cmp_le_u32_e64 s[98:99], s12, v33
	v_cmp_le_u32_e64 s[100:101], s12, v36
	v_addc_co_u32_e32 v3, vcc, 0, v3, vcc
	v_addc_co_u32_e64 v3, s[2:3], 0, v3, s[2:3]
	v_addc_co_u32_e64 v3, s[98:99], 0, v3, s[98:99]
	v_addc_co_u32_e64 v3, s[100:101], 0, v3, s[100:101]
	v_cmp_le_u32_e32 vcc, s12, v35
	v_cmp_le_u32_e64 s[2:3], s12, v38
	v_cmp_le_u32_e64 s[98:99], s12, v37
	v_cmp_le_u32_e64 s[100:101], s12, v40
	v_addc_co_u32_e32 v3, vcc, 0, v3, vcc
	v_addc_co_u32_e64 v3, s[2:3], 0, v3, s[2:3]
	v_addc_co_u32_e64 v3, s[98:99], 0, v3, s[98:99]
	v_addc_co_u32_e64 v3, s[100:101], 0, v3, s[100:101]
	s_andn2_b64 vcc, exec, s[4:5]
	s_cbranch_vccz .LBB0_2433
	s_andn2_b64 vcc, exec, s[6:7]
	s_cbranch_vccz .LBB0_2434

; __device__ __forceinline__ void dsa_item(const Params& p, int tk0) {
;     ...
;       if (nblk > 48) {
; #pragma unroll
;         for (int j = 48; j < 64; ++j) c += (sc[j] >= cand) ? 1 : 0;
;       }
.LBB0_2430:
	v_cmp_le_u32_e32 vcc, s12, v80
	v_cmp_le_u32_e64 s[2:3], s12, v82
	v_cmp_le_u32_e64 s[98:99], s12, v84
	v_cmp_le_u32_e64 s[100:101], s12, v86
	v_addc_co_u32_e32 v3, vcc, 0, v3, vcc
	v_addc_co_u32_e64 v3, s[2:3], 0, v3, s[2:3]
	v_addc_co_u32_e64 v3, s[98:99], 0, v3, s[98:99]
	v_addc_co_u32_e64 v3, s[100:101], 0, v3, s[100:101]
	v_cmp_le_u32_e32 vcc, s12, v88
	v_cmp_le_u32_e64 s[2:3], s12, v25
	v_cmp_le_u32_e64 s[98:99], s12, v23
	v_cmp_le_u32_e64 s[100:101], s12, v9
	v_addc_co_u32_e32 v3, vcc, 0, v3, vcc
	v_addc_co_u32_e64 v3, s[2:3], 0, v3, s[2:3]
	v_addc_co_u32_e64 v3, s[98:99], 0, v3, s[98:99]
	v_addc_co_u32_e64 v3, s[100:101], 0, v3, s[100:101]
	v_cmp_le_u32_e32 vcc, s12, v79
	v_cmp_le_u32_e64 s[2:3], s12, v81
	v_cmp_le_u32_e64 s[98:99], s12, v83
	v_cmp_le_u32_e64 s[100:101], s12, v85
	v_addc_co_u32_e32 v3, vcc, 0, v3, vcc
	v_addc_co_u32_e64 v3, s[2:3], 0, v3, s[2:3]
	v_addc_co_u32_e64 v3, s[98:99], 0, v3, s[98:99]
	v_addc_co_u32_e64 v3, s[100:101], 0, v3, s[100:101]
	v_cmp_le_u32_e32 vcc, s12, v87
	v_cmp_le_u32_e64 s[2:3], s12, v24
	v_cmp_le_u32_e64 s[98:99], s12, v22
	v_cmp_le_u32_e64 s[100:101], s12, v8
	v_addc_co_u32_e32 v3, vcc, 0, v3, vcc
	v_addc_co_u32_e64 v3, s[2:3], 0, v3, s[2:3]
	v_addc_co_u32_e64 v3, s[98:99], 0, v3, s[98:99]
	v_addc_co_u32_e64 v3, s[100:101], 0, v3, s[100:101]

; __device__ __forceinline__ void dsa_item(const Params& p, int tk0) {
;     ...
;       if (nblk > 16) {
; #pragma unroll
;         for (int j = 16; j < 32; ++j) c += (sc[j] >= cand) ? 1 : 0;
;       }
;       if (nblk > 32) {
; #pragma unroll
;         for (int j = 32; j < 48; ++j) c += (sc[j] >= cand) ? 1 : 0;
;       }
.LBB0_2433:
	v_cmp_le_u32_e32 vcc, s12, v42
	v_cmp_le_u32_e64 s[2:3], s12, v44
	v_cmp_le_u32_e64 s[98:99], s12, v46
	v_cmp_le_u32_e64 s[100:101], s12, v48
	v_addc_co_u32_e32 v3, vcc, 0, v3, vcc
	v_addc_co_u32_e64 v3, s[2:3], 0, v3, s[2:3]
	v_addc_co_u32_e64 v3, s[98:99], 0, v3, s[98:99]
	v_addc_co_u32_e64 v3, s[100:101], 0, v3, s[100:101]
	v_cmp_le_u32_e32 vcc, s12, v50
	v_cmp_le_u32_e64 s[2:3], s12, v52
	v_cmp_le_u32_e64 s[98:99], s12, v54
	v_cmp_le_u32_e64 s[100:101], s12, v60
	v_addc_co_u32_e32 v3, vcc, 0, v3, vcc
	v_addc_co_u32_e64 v3, s[2:3], 0, v3, s[2:3]
	v_addc_co_u32_e64 v3, s[98:99], 0, v3, s[98:99]
	v_addc_co_u32_e64 v3, s[100:101], 0, v3, s[100:101]
	v_cmp_le_u32_e32 vcc, s12, v41
	v_cmp_le_u32_e64 s[2:3], s12, v43
	v_cmp_le_u32_e64 s[98:99], s12, v45
	v_cmp_le_u32_e64 s[100:101], s12, v47
	v_addc_co_u32_e32 v3, vcc, 0, v3, vcc
	v_addc_co_u32_e64 v3, s[2:3], 0, v3, s[2:3]
	v_addc_co_u32_e64 v3, s[98:99], 0, v3, s[98:99]
	v_addc_co_u32_e64 v3, s[100:101], 0, v3, s[100:101]
	v_cmp_le_u32_e32 vcc, s12, v49
	v_cmp_le_u32_e64 s[2:3], s12, v51
	v_cmp_le_u32_e64 s[98:99], s12, v53
	v_cmp_le_u32_e64 s[100:101], s12, v59
	v_addc_co_u32_e32 v3, vcc, 0, v3, vcc
	v_addc_co_u32_e64 v3, s[2:3], 0, v3, s[2:3]
	v_addc_co_u32_e64 v3, s[98:99], 0, v3, s[98:99]
	v_addc_co_u32_e64 v3, s[100:101], 0, v3, s[100:101]
	s_andn2_b64 vcc, exec, s[6:7]
	s_cbranch_vccnz .LBB0_2429
.LBB0_2434:
	v_cmp_le_u32_e32 vcc, s12, v64
	v_cmp_le_u32_e64 s[2:3], s12, v66
	v_cmp_le_u32_e64 s[98:99], s12, v68
	v_cmp_le_u32_e64 s[100:101], s12, v70
	v_addc_co_u32_e32 v3, vcc, 0, v3, vcc
	v_addc_co_u32_e64 v3, s[2:3], 0, v3, s[2:3]
	v_addc_co_u32_e64 v3, s[98:99], 0, v3, s[98:99]
	v_addc_co_u32_e64 v3, s[100:101], 0, v3, s[100:101]
	v_cmp_le_u32_e32 vcc, s12, v72
	v_cmp_le_u32_e64 s[2:3], s12, v74
	v_cmp_le_u32_e64 s[98:99], s12, v76
	v_cmp_le_u32_e64 s[100:101], s12, v78
	v_addc_co_u32_e32 v3, vcc, 0, v3, vcc
	v_addc_co_u32_e64 v3, s[2:3], 0, v3, s[2:3]
	v_addc_co_u32_e64 v3, s[98:99], 0, v3, s[98:99]
	v_addc_co_u32_e64 v3, s[100:101], 0, v3, s[100:101]
	v_cmp_le_u32_e32 vcc, s12, v63
	v_cmp_le_u32_e64 s[2:3], s12, v65
	v_cmp_le_u32_e64 s[98:99], s12, v67
	v_cmp_le_u32_e64 s[100:101], s12, v69
	v_addc_co_u32_e32 v3, vcc, 0, v3, vcc
	v_addc_co_u32_e64 v3, s[2:3], 0, v3, s[2:3]
	v_addc_co_u32_e64 v3, s[98:99], 0, v3, s[98:99]
	v_addc_co_u32_e64 v3, s[100:101], 0, v3, s[100:101]
	v_cmp_le_u32_e32 vcc, s12, v71
	v_cmp_le_u32_e64 s[2:3], s12, v73
	v_cmp_le_u32_e64 s[98:99], s12, v75
	v_cmp_le_u32_e64 s[100:101], s12, v77
	v_addc_co_u32_e32 v3, vcc, 0, v3, vcc
	v_addc_co_u32_e64 v3, s[2:3], 0, v3, s[2:3]
	v_addc_co_u32_e64 v3, s[98:99], 0, v3, s[98:99]
	v_addc_co_u32_e64 v3, s[100:101], 0, v3, s[100:101]
	s_andn2_b64 vcc, exec, s[8:9]
	s_cbranch_vccz .LBB0_2430
	s_branch .LBB0_2431

; __global__ void __launch_bounds__(NTHREADS) fwd_megakernel(Params p) {
	.amdhsa_kernel _Z14fwd_megakernel6Params
		.amdhsa_group_segment_fixed_size 16
		.amdhsa_private_segment_fixed_size 0
		.amdhsa_kernarg_size 392
		.amdhsa_user_sgpr_count 2
		.amdhsa_user_sgpr_dispatch_ptr 0
		.amdhsa_user_sgpr_queue_ptr 0
		.amdhsa_user_sgpr_kernarg_segment_ptr 1
		.amdhsa_user_sgpr_dispatch_id 0
		.amdhsa_user_sgpr_kernarg_preload_length 0
		.amdhsa_user_sgpr_kernarg_preload_offset 0
		.amdhsa_user_sgpr_private_segment_size 0
		.amdhsa_uses_dynamic_stack 0
		.amdhsa_enable_private_segment 0
		.amdhsa_system_sgpr_workgroup_id_x 1
		.amdhsa_system_sgpr_workgroup_id_y 0
		.amdhsa_system_sgpr_workgroup_id_z 0
		.amdhsa_system_sgpr_workgroup_info 0
		.amdhsa_system_vgpr_workitem_id 2
		.amdhsa_next_free_vgpr 256
		.amdhsa_next_free_sgpr 102
		.amdhsa_accum_offset 256
		.amdhsa_reserve_vcc 1
		.amdhsa_float_round_mode_32 0
		.amdhsa_float_round_mode_16_64 0
		.amdhsa_float_denorm_mode_32 3
		.amdhsa_float_denorm_mode_16_64 3
		.amdhsa_dx10_clamp 1
		.amdhsa_ieee_mode 1
		.amdhsa_fp16_overflow 0
		.amdhsa_tg_split 0
		.amdhsa_exception_fp_ieee_invalid_op 0
		.amdhsa_exception_fp_denorm_src 0
		.amdhsa_exception_fp_ieee_div_zero 0
		.amdhsa_exception_fp_ieee_overflow 0
		.amdhsa_exception_fp_ieee_underflow 0
		.amdhsa_exception_fp_ieee_inexact 0
		.amdhsa_exception_int_div_zero 0
	.end_amdhsa_kernel

; __global__ void __launch_bounds__(NTHREADS) fwd_megakernel(Params p) {
amdhsa.kernels:
  - .agpr_count:     0
    .args:
      - .offset:         0
        .size:           136
        .value_kind:     by_value
      - .offset:         136
        .size:           4
        .value_kind:     hidden_block_count_x
      - .offset:         140
        .size:           4
        .value_kind:     hidden_block_count_y
      - .offset:         144
        .size:           4
        .value_kind:     hidden_block_count_z
      - .offset:         148
        .size:           2
        .value_kind:     hidden_group_size_x
      - .offset:         150
        .size:           2
        .value_kind:     hidden_group_size_y
      - .offset:         152
        .size:           2
        .value_kind:     hidden_group_size_z
      - .offset:         154
        .size:           2
        .value_kind:     hidden_remainder_x
      - .offset:         156
        .size:           2
        .value_kind:     hidden_remainder_y
      - .offset:         158
        .size:           2
        .value_kind:     hidden_remainder_z
      - .offset:         176
        .size:           8
        .value_kind:     hidden_global_offset_x
      - .offset:         184
        .size:           8
        .value_kind:     hidden_global_offset_y
      - .offset:         192
        .size:           8
        .value_kind:     hidden_global_offset_z
      - .offset:         200
        .size:           2
        .value_kind:     hidden_grid_dims
      - .offset:         224
        .size:           8
        .value_kind:     hidden_multigrid_sync_arg
      - .offset:         256
        .size:           4
        .value_kind:     hidden_dynamic_lds_size
    .group_segment_fixed_size: 16
    .kernarg_segment_align: 8
    .kernarg_segment_size: 392
    .language:       OpenCL C
    .language_version:
      - 2
      - 0
    .max_flat_workgroup_size: 512
    .name:           _Z14fwd_megakernel6Params
    .private_segment_fixed_size: 0
    .sgpr_count:     108
    .sgpr_spill_count: 130
    .symbol:         _Z14fwd_megakernel6Params.kd
    .uniform_work_group_size: 1
    .uses_dynamic_stack: false
    .vgpr_count:     256
    .vgpr_spill_count: 0
    .wavefront_size: 64
